# P4b conv edge fix-up: G==256 fast path, six items per thread unrolled with all loads in flight (on top of PV rewrite)
# speedup vs baseline: 1.0678x; 1.0026x over previous
.LBB0_653:
	s_or_b64 exec, exec, s[6:7]
	v_lshl_add_u32 v24, s33, 9, v172
	s_mov_b32 s2, 0xb0000
	v_cmp_gt_i32_e32 vcc, s2, v24
	s_waitcnt lgkmcnt(0)
	s_barrier
	s_and_saveexec_b64 s[6:7], vcc
	s_cbranch_execz .LBB0_666
	s_cmp_eq_u32 s3, 0x100
	s_cbranch_scc0 .Lp4b_generic
	s_load_dwordx2 s[10:11], s[0:1], 0xb0
	s_load_dwordx2 s[8:9], s[0:1], 0x70
	s_mov_b32 s22, 0x2e8ba2e9
	s_mov_b32 s12, 0x3dd2d3e8
	s_movk_i32 s23, 0x2c00
	s_mov_b32 s24, 0x10000
	v_mov_b32_e32 v16, 0xc0135761
	s_waitcnt lgkmcnt(0)
	s_add_u32 s14, s10, 0x6800000
	s_addc_u32 s15, s11, 0
	s_add_u32 s16, s14, 0x2c00
	s_addc_u32 s17, s15, 0
	s_add_u32 s18, s10, 0x12800000
	s_addc_u32 s19, s11, 0
	v_mov_b32_e32 v0, v24
	v_mul_hi_u32 v1, v0, s22
	v_lshrrev_b32_e32 v1, 7, v1
	v_mul_u32_u24_e32 v2, 0x2c0, v1
	v_sub_u32_e32 v3, v0, v2
	v_lshlrev_b32_e32 v4, 4, v3
	v_mul_u32_u24_e32 v5, 3, v1
	v_mad_u32_u24 v6, v5, s23, v4
	v_and_b32_e32 v7, 1, v1
	v_lshrrev_b32_e32 v8, 1, v1
	v_add_u32_e32 v10, v8, v7
	v_and_b32_e32 v10, 31, v10
	v_cmp_ne_u32_e32 vcc, 0, v10
	v_mul_u32_u24_e32 v9, 0x10800, v7
	v_add_u32_e32 v9, 0xffffd400, v9
	v_mul_u32_u24_e32 v11, 0x5800, v7
	v_cndmask_b32_e32 v9, 0, v9, vcc
	v_cndmask_b32_e64 v50, 0, 1.0, vcc
	v_add_u32_e32 v9, v6, v9
	v_add_u32_e32 v11, v11, v4
	v_lshlrev_b32_e32 v12, 6, v8
	v_mad_u32_u24 v12, v7, 63, v12
	v_mul_u32_u24_e32 v13, 0x1600, v12
	v_lshrrev_b32_e32 v14, 1, v4
	v_add_u32_e32 v48, v13, v14
	global_load_dwordx4 v[32:35], v6, s[14:15]
	global_load_dwordx4 v[36:39], v6, s[16:17]
	global_load_dwordx4 v[40:43], v9, s[14:15]
	global_load_dwordx4 v[44:47], v11, s[8:9]
	v_add_u32_e32 v0, 0x20000, v24
	v_mul_hi_u32 v1, v0, s22
	v_lshrrev_b32_e32 v1, 7, v1
	v_mul_u32_u24_e32 v2, 0x2c0, v1
	v_sub_u32_e32 v3, v0, v2
	v_lshlrev_b32_e32 v4, 4, v3
	v_mul_u32_u24_e32 v5, 3, v1
	v_mad_u32_u24 v6, v5, s23, v4
	v_and_b32_e32 v7, 1, v1
	v_lshrrev_b32_e32 v8, 1, v1
	v_add_u32_e32 v10, v8, v7
	v_and_b32_e32 v10, 31, v10
	v_cmp_ne_u32_e32 vcc, 0, v10
	v_mul_u32_u24_e32 v9, 0x10800, v7
	v_add_u32_e32 v9, 0xffffd400, v9
	v_mul_u32_u24_e32 v11, 0x5800, v7
	v_cndmask_b32_e32 v9, 0, v9, vcc
	v_cndmask_b32_e64 v70, 0, 1.0, vcc
	v_add_u32_e32 v9, v6, v9
	v_add_u32_e32 v11, v11, v4
	v_lshlrev_b32_e32 v12, 6, v8
	v_mad_u32_u24 v12, v7, 63, v12
	v_mul_u32_u24_e32 v13, 0x1600, v12
	v_lshrrev_b32_e32 v14, 1, v4
	v_add_u32_e32 v68, v13, v14
	global_load_dwordx4 v[52:55], v6, s[14:15]
	global_load_dwordx4 v[56:59], v6, s[16:17]
	global_load_dwordx4 v[60:63], v9, s[14:15]
	global_load_dwordx4 v[64:67], v11, s[8:9]
	v_add_u32_e32 v0, 0x40000, v24
	v_mul_hi_u32 v1, v0, s22
	v_lshrrev_b32_e32 v1, 7, v1
	v_mul_u32_u24_e32 v2, 0x2c0, v1
	v_sub_u32_e32 v3, v0, v2
	v_lshlrev_b32_e32 v4, 4, v3
	v_mul_u32_u24_e32 v5, 3, v1
	v_mad_u32_u24 v6, v5, s23, v4
	v_and_b32_e32 v7, 1, v1
	v_lshrrev_b32_e32 v8, 1, v1
	v_add_u32_e32 v10, v8, v7
	v_and_b32_e32 v10, 31, v10
	v_cmp_ne_u32_e32 vcc, 0, v10
	v_mul_u32_u24_e32 v9, 0x10800, v7
	v_add_u32_e32 v9, 0xffffd400, v9
	v_mul_u32_u24_e32 v11, 0x5800, v7
	v_cndmask_b32_e32 v9, 0, v9, vcc
	v_cndmask_b32_e64 v90, 0, 1.0, vcc
	v_add_u32_e32 v9, v6, v9
	v_add_u32_e32 v11, v11, v4
	v_lshlrev_b32_e32 v12, 6, v8
	v_mad_u32_u24 v12, v7, 63, v12
	v_mul_u32_u24_e32 v13, 0x1600, v12
	v_lshrrev_b32_e32 v14, 1, v4
	v_add_u32_e32 v88, v13, v14
	global_load_dwordx4 v[72:75], v6, s[14:15]
	global_load_dwordx4 v[76:79], v6, s[16:17]
	global_load_dwordx4 v[80:83], v9, s[14:15]
	global_load_dwordx4 v[84:87], v11, s[8:9]
	v_add_u32_e32 v0, 0x60000, v24
	v_mul_hi_u32 v1, v0, s22
	v_lshrrev_b32_e32 v1, 7, v1
	v_mul_u32_u24_e32 v2, 0x2c0, v1
	v_sub_u32_e32 v3, v0, v2
	v_lshlrev_b32_e32 v4, 4, v3
	v_mul_u32_u24_e32 v5, 3, v1
	v_mad_u32_u24 v6, v5, s23, v4
	v_and_b32_e32 v7, 1, v1
	v_lshrrev_b32_e32 v8, 1, v1
	v_add_u32_e32 v10, v8, v7
	v_and_b32_e32 v10, 31, v10
	v_cmp_ne_u32_e32 vcc, 0, v10
	v_mul_u32_u24_e32 v9, 0x10800, v7
	v_add_u32_e32 v9, 0xffffd400, v9
	v_mul_u32_u24_e32 v11, 0x5800, v7
	v_cndmask_b32_e32 v9, 0, v9, vcc
	v_cndmask_b32_e64 v110, 0, 1.0, vcc
	v_add_u32_e32 v9, v6, v9
	v_add_u32_e32 v11, v11, v4
	v_lshlrev_b32_e32 v12, 6, v8
	v_mad_u32_u24 v12, v7, 63, v12
	v_mul_u32_u24_e32 v13, 0x1600, v12
	v_lshrrev_b32_e32 v14, 1, v4
	v_add_u32_e32 v108, v13, v14
	global_load_dwordx4 v[92:95], v6, s[14:15]
	global_load_dwordx4 v[96:99], v6, s[16:17]
	global_load_dwordx4 v[100:103], v9, s[14:15]
	global_load_dwordx4 v[104:107], v11, s[8:9]
	v_add_u32_e32 v0, 0x80000, v24
	v_mul_hi_u32 v1, v0, s22
	v_lshrrev_b32_e32 v1, 7, v1
	v_mul_u32_u24_e32 v2, 0x2c0, v1
	v_sub_u32_e32 v3, v0, v2
	v_lshlrev_b32_e32 v4, 4, v3
	v_mul_u32_u24_e32 v5, 3, v1
	v_mad_u32_u24 v6, v5, s23, v4
	v_and_b32_e32 v7, 1, v1
	v_lshrrev_b32_e32 v8, 1, v1
	v_add_u32_e32 v10, v8, v7
	v_and_b32_e32 v10, 31, v10
	v_cmp_ne_u32_e32 vcc, 0, v10
	v_mul_u32_u24_e32 v9, 0x10800, v7
	v_add_u32_e32 v9, 0xffffd400, v9
	v_mul_u32_u24_e32 v11, 0x5800, v7
	v_cndmask_b32_e32 v9, 0, v9, vcc
	v_cndmask_b32_e64 v130, 0, 1.0, vcc
	v_add_u32_e32 v9, v6, v9
	v_add_u32_e32 v11, v11, v4
	v_lshlrev_b32_e32 v12, 6, v8
	v_mad_u32_u24 v12, v7, 63, v12
	v_mul_u32_u24_e32 v13, 0x1600, v12
	v_lshrrev_b32_e32 v14, 1, v4
	v_add_u32_e32 v128, v13, v14
	global_load_dwordx4 v[112:115], v6, s[14:15]
	global_load_dwordx4 v[116:119], v6, s[16:17]
	global_load_dwordx4 v[120:123], v9, s[14:15]
	global_load_dwordx4 v[124:127], v11, s[8:9]
	v_add_u32_e32 v0, 0xa0000, v24
	v_cmp_gt_u32_e32 vcc, s24, v24
	s_nop 1
	v_cndmask_b32_e32 v0, v24, v0, vcc
	v_mul_hi_u32 v1, v0, s22
	v_lshrrev_b32_e32 v1, 7, v1
	v_mul_u32_u24_e32 v2, 0x2c0, v1
	v_sub_u32_e32 v3, v0, v2
	v_lshlrev_b32_e32 v4, 4, v3
	v_mul_u32_u24_e32 v5, 3, v1
	v_mad_u32_u24 v6, v5, s23, v4
	v_and_b32_e32 v7, 1, v1
	v_lshrrev_b32_e32 v8, 1, v1
	v_add_u32_e32 v10, v8, v7
	v_and_b32_e32 v10, 31, v10
	v_cmp_ne_u32_e32 vcc, 0, v10
	v_mul_u32_u24_e32 v9, 0x10800, v7
	v_add_u32_e32 v9, 0xffffd400, v9
	v_mul_u32_u24_e32 v11, 0x5800, v7
	v_cndmask_b32_e32 v9, 0, v9, vcc
	v_cndmask_b32_e64 v150, 0, 1.0, vcc
	v_add_u32_e32 v9, v6, v9
	v_add_u32_e32 v11, v11, v4
	v_lshlrev_b32_e32 v12, 6, v8
	v_mad_u32_u24 v12, v7, 63, v12
	v_mul_u32_u24_e32 v13, 0x1600, v12
	v_lshrrev_b32_e32 v14, 1, v4
	v_add_u32_e32 v148, v13, v14
	global_load_dwordx4 v[132:135], v6, s[14:15]
	global_load_dwordx4 v[136:139], v6, s[16:17]
	global_load_dwordx4 v[140:143], v9, s[14:15]
	global_load_dwordx4 v[144:147], v11, s[8:9]
	s_waitcnt vmcnt(20)
	v_pk_mul_f32 v[44:45], v[44:45], v[50:51] op_sel_hi:[1,0]
	v_pk_mul_f32 v[46:47], v[46:47], v[50:51] op_sel_hi:[1,0]
	v_pk_fma_f32 v[4:5], v[40:41], v[44:45], v[32:33]
	v_pk_fma_f32 v[6:7], v[42:43], v[46:47], v[34:35]
	v_pk_mul_f32 v[10:11], v[4:5], v[4:5]
	v_pk_mul_f32 v[8:9], v[6:7], v[6:7]
	v_pk_fma_f32 v[10:11], v[10:11], s[12:13], v[16:17] op_sel_hi:[1,0,0] neg_lo:[1,0,0] neg_hi:[1,0,0]
	v_pk_fma_f32 v[8:9], v[8:9], s[12:13], v[16:17] op_sel_hi:[1,0,0] neg_lo:[1,0,0] neg_hi:[1,0,0]
	v_pk_mul_f32 v[10:11], v[4:5], v[10:11]
	v_pk_mul_f32 v[8:9], v[6:7], v[8:9]
	v_exp_f32_e32 v10, v10
	v_exp_f32_e32 v11, v11
	v_exp_f32_e32 v8, v8
	v_exp_f32_e32 v9, v9
	s_nop 0
	v_pk_add_f32 v[10:11], v[10:11], 1.0 op_sel_hi:[1,0]
	v_pk_add_f32 v[8:9], v[8:9], 1.0 op_sel_hi:[1,0]
	v_rcp_f32_e32 v10, v10
	v_rcp_f32_e32 v11, v11
	v_rcp_f32_e32 v8, v8
	v_rcp_f32_e32 v9, v9
	s_nop 0
	v_pk_mul_f32 v[4:5], v[4:5], v[10:11]
	v_pk_mul_f32 v[6:7], v[6:7], v[8:9]
	v_pk_mul_f32 v[0:1], v[36:37], v[4:5]
	v_pk_mul_f32 v[2:3], v[38:39], v[6:7]
	s_nop 0
	v_cvt_pk_bf16_f32 v0, v0, v1
	v_cvt_pk_bf16_f32 v1, v2, v3
	s_nop 0
	global_store_dwordx2 v48, v[0:1], s[18:19]
	s_waitcnt vmcnt(17)
	v_pk_mul_f32 v[64:65], v[64:65], v[70:71] op_sel_hi:[1,0]
	v_pk_mul_f32 v[66:67], v[66:67], v[70:71] op_sel_hi:[1,0]
	v_pk_fma_f32 v[4:5], v[60:61], v[64:65], v[52:53]
	v_pk_fma_f32 v[6:7], v[62:63], v[66:67], v[54:55]
	v_pk_mul_f32 v[10:11], v[4:5], v[4:5]
	v_pk_mul_f32 v[8:9], v[6:7], v[6:7]
	v_pk_fma_f32 v[10:11], v[10:11], s[12:13], v[16:17] op_sel_hi:[1,0,0] neg_lo:[1,0,0] neg_hi:[1,0,0]
	v_pk_fma_f32 v[8:9], v[8:9], s[12:13], v[16:17] op_sel_hi:[1,0,0] neg_lo:[1,0,0] neg_hi:[1,0,0]
	v_pk_mul_f32 v[10:11], v[4:5], v[10:11]
	v_pk_mul_f32 v[8:9], v[6:7], v[8:9]
	v_exp_f32_e32 v10, v10
	v_exp_f32_e32 v11, v11
	v_exp_f32_e32 v8, v8
	v_exp_f32_e32 v9, v9
	s_nop 0
	v_pk_add_f32 v[10:11], v[10:11], 1.0 op_sel_hi:[1,0]
	v_pk_add_f32 v[8:9], v[8:9], 1.0 op_sel_hi:[1,0]
	v_rcp_f32_e32 v10, v10
	v_rcp_f32_e32 v11, v11
	v_rcp_f32_e32 v8, v8
	v_rcp_f32_e32 v9, v9
	s_nop 0
	v_pk_mul_f32 v[4:5], v[4:5], v[10:11]
	v_pk_mul_f32 v[6:7], v[6:7], v[8:9]
	v_pk_mul_f32 v[0:1], v[56:57], v[4:5]
	v_pk_mul_f32 v[2:3], v[58:59], v[6:7]
	s_nop 0
	v_cvt_pk_bf16_f32 v0, v0, v1
	v_cvt_pk_bf16_f32 v1, v2, v3
	s_nop 0
	global_store_dwordx2 v68, v[0:1], s[18:19]
	s_waitcnt vmcnt(14)
	v_pk_mul_f32 v[84:85], v[84:85], v[90:91] op_sel_hi:[1,0]
	v_pk_mul_f32 v[86:87], v[86:87], v[90:91] op_sel_hi:[1,0]
	v_pk_fma_f32 v[4:5], v[80:81], v[84:85], v[72:73]
	v_pk_fma_f32 v[6:7], v[82:83], v[86:87], v[74:75]
	v_pk_mul_f32 v[10:11], v[4:5], v[4:5]
	v_pk_mul_f32 v[8:9], v[6:7], v[6:7]
	v_pk_fma_f32 v[10:11], v[10:11], s[12:13], v[16:17] op_sel_hi:[1,0,0] neg_lo:[1,0,0] neg_hi:[1,0,0]
	v_pk_fma_f32 v[8:9], v[8:9], s[12:13], v[16:17] op_sel_hi:[1,0,0] neg_lo:[1,0,0] neg_hi:[1,0,0]
	v_pk_mul_f32 v[10:11], v[4:5], v[10:11]
	v_pk_mul_f32 v[8:9], v[6:7], v[8:9]
	v_exp_f32_e32 v10, v10
	v_exp_f32_e32 v11, v11
	v_exp_f32_e32 v8, v8
	v_exp_f32_e32 v9, v9
	s_nop 0
	v_pk_add_f32 v[10:11], v[10:11], 1.0 op_sel_hi:[1,0]
	v_pk_add_f32 v[8:9], v[8:9], 1.0 op_sel_hi:[1,0]
	v_rcp_f32_e32 v10, v10
	v_rcp_f32_e32 v11, v11
	v_rcp_f32_e32 v8, v8
	v_rcp_f32_e32 v9, v9
	s_nop 0
	v_pk_mul_f32 v[4:5], v[4:5], v[10:11]
	v_pk_mul_f32 v[6:7], v[6:7], v[8:9]
	v_pk_mul_f32 v[0:1], v[76:77], v[4:5]
	v_pk_mul_f32 v[2:3], v[78:79], v[6:7]
	s_nop 0
	v_cvt_pk_bf16_f32 v0, v0, v1
	v_cvt_pk_bf16_f32 v1, v2, v3
	s_nop 0
	global_store_dwordx2 v88, v[0:1], s[18:19]
	s_waitcnt vmcnt(11)
	v_pk_mul_f32 v[104:105], v[104:105], v[110:111] op_sel_hi:[1,0]
	v_pk_mul_f32 v[106:107], v[106:107], v[110:111] op_sel_hi:[1,0]
	v_pk_fma_f32 v[4:5], v[100:101], v[104:105], v[92:93]
	v_pk_fma_f32 v[6:7], v[102:103], v[106:107], v[94:95]
	v_pk_mul_f32 v[10:11], v[4:5], v[4:5]
	v_pk_mul_f32 v[8:9], v[6:7], v[6:7]
	v_pk_fma_f32 v[10:11], v[10:11], s[12:13], v[16:17] op_sel_hi:[1,0,0] neg_lo:[1,0,0] neg_hi:[1,0,0]
	v_pk_fma_f32 v[8:9], v[8:9], s[12:13], v[16:17] op_sel_hi:[1,0,0] neg_lo:[1,0,0] neg_hi:[1,0,0]
	v_pk_mul_f32 v[10:11], v[4:5], v[10:11]
	v_pk_mul_f32 v[8:9], v[6:7], v[8:9]
	v_exp_f32_e32 v10, v10
	v_exp_f32_e32 v11, v11
	v_exp_f32_e32 v8, v8
	v_exp_f32_e32 v9, v9
	s_nop 0
	v_pk_add_f32 v[10:11], v[10:11], 1.0 op_sel_hi:[1,0]
	v_pk_add_f32 v[8:9], v[8:9], 1.0 op_sel_hi:[1,0]
	v_rcp_f32_e32 v10, v10
	v_rcp_f32_e32 v11, v11
	v_rcp_f32_e32 v8, v8
	v_rcp_f32_e32 v9, v9
	s_nop 0
	v_pk_mul_f32 v[4:5], v[4:5], v[10:11]
	v_pk_mul_f32 v[6:7], v[6:7], v[8:9]
	v_pk_mul_f32 v[0:1], v[96:97], v[4:5]
	v_pk_mul_f32 v[2:3], v[98:99], v[6:7]
	s_nop 0
	v_cvt_pk_bf16_f32 v0, v0, v1
	v_cvt_pk_bf16_f32 v1, v2, v3
	s_nop 0
	global_store_dwordx2 v108, v[0:1], s[18:19]
	s_waitcnt vmcnt(8)
	v_pk_mul_f32 v[124:125], v[124:125], v[130:131] op_sel_hi:[1,0]
	v_pk_mul_f32 v[126:127], v[126:127], v[130:131] op_sel_hi:[1,0]
	v_pk_fma_f32 v[4:5], v[120:121], v[124:125], v[112:113]
	v_pk_fma_f32 v[6:7], v[122:123], v[126:127], v[114:115]
	v_pk_mul_f32 v[10:11], v[4:5], v[4:5]
	v_pk_mul_f32 v[8:9], v[6:7], v[6:7]
	v_pk_fma_f32 v[10:11], v[10:11], s[12:13], v[16:17] op_sel_hi:[1,0,0] neg_lo:[1,0,0] neg_hi:[1,0,0]
	v_pk_fma_f32 v[8:9], v[8:9], s[12:13], v[16:17] op_sel_hi:[1,0,0] neg_lo:[1,0,0] neg_hi:[1,0,0]
	v_pk_mul_f32 v[10:11], v[4:5], v[10:11]
	v_pk_mul_f32 v[8:9], v[6:7], v[8:9]
	v_exp_f32_e32 v10, v10
	v_exp_f32_e32 v11, v11
	v_exp_f32_e32 v8, v8
	v_exp_f32_e32 v9, v9
	s_nop 0
	v_pk_add_f32 v[10:11], v[10:11], 1.0 op_sel_hi:[1,0]
	v_pk_add_f32 v[8:9], v[8:9], 1.0 op_sel_hi:[1,0]
	v_rcp_f32_e32 v10, v10
	v_rcp_f32_e32 v11, v11
	v_rcp_f32_e32 v8, v8
	v_rcp_f32_e32 v9, v9
	s_nop 0
	v_pk_mul_f32 v[4:5], v[4:5], v[10:11]
	v_pk_mul_f32 v[6:7], v[6:7], v[8:9]
	v_pk_mul_f32 v[0:1], v[116:117], v[4:5]
	v_pk_mul_f32 v[2:3], v[118:119], v[6:7]
	s_nop 0
	v_cvt_pk_bf16_f32 v0, v0, v1
	v_cvt_pk_bf16_f32 v1, v2, v3
	s_nop 0
	global_store_dwordx2 v128, v[0:1], s[18:19]
	s_waitcnt vmcnt(5)
	v_pk_mul_f32 v[144:145], v[144:145], v[150:151] op_sel_hi:[1,0]
	v_pk_mul_f32 v[146:147], v[146:147], v[150:151] op_sel_hi:[1,0]
	v_pk_fma_f32 v[4:5], v[140:141], v[144:145], v[132:133]
	v_pk_fma_f32 v[6:7], v[142:143], v[146:147], v[134:135]
	v_pk_mul_f32 v[10:11], v[4:5], v[4:5]
	v_pk_mul_f32 v[8:9], v[6:7], v[6:7]
	v_pk_fma_f32 v[10:11], v[10:11], s[12:13], v[16:17] op_sel_hi:[1,0,0] neg_lo:[1,0,0] neg_hi:[1,0,0]
	v_pk_fma_f32 v[8:9], v[8:9], s[12:13], v[16:17] op_sel_hi:[1,0,0] neg_lo:[1,0,0] neg_hi:[1,0,0]
	v_pk_mul_f32 v[10:11], v[4:5], v[10:11]
	v_pk_mul_f32 v[8:9], v[6:7], v[8:9]
	v_exp_f32_e32 v10, v10
	v_exp_f32_e32 v11, v11
	v_exp_f32_e32 v8, v8
	v_exp_f32_e32 v9, v9
	s_nop 0
	v_pk_add_f32 v[10:11], v[10:11], 1.0 op_sel_hi:[1,0]
	v_pk_add_f32 v[8:9], v[8:9], 1.0 op_sel_hi:[1,0]
	v_rcp_f32_e32 v10, v10
	v_rcp_f32_e32 v11, v11
	v_rcp_f32_e32 v8, v8
	v_rcp_f32_e32 v9, v9
	s_nop 0
	v_pk_mul_f32 v[4:5], v[4:5], v[10:11]
	v_pk_mul_f32 v[6:7], v[6:7], v[8:9]
	v_pk_mul_f32 v[0:1], v[136:137], v[4:5]
	v_pk_mul_f32 v[2:3], v[138:139], v[6:7]
	s_nop 0
	v_cvt_pk_bf16_f32 v0, v0, v1
	v_cvt_pk_bf16_f32 v1, v2, v3
	s_nop 0
	v_cmp_gt_u32_e32 vcc, s24, v24
	s_nop 1
	s_and_saveexec_b64 s[20:21], vcc
	global_store_dwordx2 v148, v[0:1], s[18:19]
	s_or_b64 exec, exec, s[20:21]
	s_branch .LBB0_666
.Lp4b_generic:
	s_load_dwordx2 s[10:11], s[0:1], 0xb0
	s_load_dwordx2 s[8:9], s[0:1], 0x70
	v_lshlrev_b32_e32 v25, 2, v24
	s_mov_b32 s22, 0x2e8ba2e9
	s_movk_i32 s23, 0x2c00
	s_waitcnt lgkmcnt(0)
	s_add_u32 s14, s10, 0x6800000
	s_addc_u32 s15, s11, 0
	s_add_u32 s16, s10, 0x12800000
	s_addc_u32 s17, s11, 0
	v_mov_b64_e32 v[12:13], s[14:15]
	s_mov_b32 s14, 0xc0135761
	s_lshl_b32 s2, s3, 9
	s_lshl_b32 s13, s3, 11
	s_mov_b64 s[10:11], 0
	s_movk_i32 s24, 0x7ff
	v_mov_b32_e32 v15, 0
	s_mov_b32 s12, 0x3dd2d3e8
	v_mov_b64_e32 v[16:17], s[14:15]
	s_movk_i32 s25, 0x1600
	v_mov_b64_e32 v[18:19], s[16:17]
	s_mov_b32 s31, 0xaffff
	s_branch .LBB0_656
